# attention fast paths (FAR / MID / STR512): the first eight V fragments of P.V are read right after the score selection, under the softmax, instead of at the head of the P.V block
# speedup vs baseline: 1.0089x; 1.0017x over previous
; template <int KS, int HF>
; __device__ __forceinline__ void pv_tile(f32x16* o, int vb, bf16x8 pa0, bf16x8 pa1, bf16x8 pa2, bf16x8 pa3) {
; __device__ __forceinline__ void attn_block(const bf16_t* __restrict__ proj, bf16_t* __restrict__ mixed, int b, int h, int qb, char* lds) {
;     ...
;                 const float NEG = -__builtin_inff();
;                 float e0 = FA_SEL8(p0, 0) + fc0, e1 = FA_SEL8(p0, 8) + (fc0 + 16.f * slr), e2 = FA_SEL8(p1, 0) + (fc0 + 32.f * slr), e3 = FA_SEL8(p1, 8) + (fc0 + 48.f * slr);
;     ...
;                 e0 = lane_valid ? e0 : NEG; e1 = lane_valid ? e1 : NEG; e2 = lane_valid ? e2 : NEG; e3 = lane_valid ? e3 : NEG;
;                 float pmax = fmaxf(fmaxf(e0, e1), fmaxf(e2, e3));
;                 { auto rr = __builtin_amdgcn_permlane32_swap(__float_as_uint(pmax), __float_as_uint(pmax), false, false); pmax = fmaxf(__uint_as_float(rr[0]), __uint_as_float(rr[1])); }
;                 constexpr float C2 = LOG2E * SCALE; float mn;
;                 if (__builtin_expect(__all((pmax - m_reg) * SCALE <= THR), 1)) { mn = m_reg; alpha = 1.f; }
;                 else { mn = fmaxf(m_reg, pmax); alpha = __builtin_amdgcn_exp2f((m_reg - mn) * C2); m_reg = mn; }
;                 const float mnL = -mn * C2;
;                 e0 = __builtin_amdgcn_exp2f(__builtin_fmaf(e0, C2, mnL)); e1 = __builtin_amdgcn_exp2f(__builtin_fmaf(e1, C2, mnL));
;                 e2 = __builtin_amdgcn_exp2f(__builtin_fmaf(e2, C2, mnL)); e3 = __builtin_amdgcn_exp2f(__builtin_fmaf(e3, C2, mnL));
;                 float ps = (e0 + e1) + (e2 + e3);
;                 { auto rr = __builtin_amdgcn_permlane32_swap(__float_as_uint(ps), __float_as_uint(ps), false, false); ps = __uint_as_float(rr[0]) + __uint_as_float(rr[1]); }
;                 l_reg = l_reg * alpha + ps;
;     ...
;                 FA_SCAT(e0, pa0); FA_SCAT(e1, pa1); FA_SCAT(e2, pa2); FA_SCAT(e3, pa3);
.Lmid_fast:
	s_nop 3
	v_and_b32_e32 v132, 3, v0
	v_and_b32_e32 v134, 12, v0
	v_cvt_f32_u32_e32 v133, v132
	v_cmp_eq_u32_e32 vcc, 1, v132
	v_cndmask_b32_e32 v116, v96, v97, vcc
	v_cndmask_b32_e32 v117, v100, v101, vcc
	v_cndmask_b32_e32 v118, v104, v105, vcc
	v_cndmask_b32_e32 v119, v108, v109, vcc
	v_cndmask_b32_e32 v120, v80, v81, vcc
	v_cndmask_b32_e32 v121, v84, v85, vcc
	v_cndmask_b32_e32 v122, v88, v89, vcc
	v_cndmask_b32_e32 v123, v92, v93, vcc
	v_cmp_eq_u32_e32 vcc, 2, v132
	v_cndmask_b32_e32 v116, v116, v98, vcc
	v_cndmask_b32_e32 v117, v117, v102, vcc
	v_cndmask_b32_e32 v118, v118, v106, vcc
	v_cndmask_b32_e32 v119, v119, v110, vcc
	v_cndmask_b32_e32 v120, v120, v82, vcc
	v_cndmask_b32_e32 v121, v121, v86, vcc
	v_cndmask_b32_e32 v122, v122, v90, vcc
	v_cndmask_b32_e32 v123, v123, v94, vcc
	v_cmp_eq_u32_e32 vcc, 3, v132
	v_cndmask_b32_e32 v116, v116, v99, vcc
	v_cndmask_b32_e32 v117, v117, v103, vcc
	v_cndmask_b32_e32 v118, v118, v107, vcc
	v_cndmask_b32_e32 v119, v119, v111, vcc
	v_cndmask_b32_e32 v120, v120, v83, vcc
	v_cndmask_b32_e32 v121, v121, v87, vcc
	v_cndmask_b32_e32 v122, v122, v91, vcc
	v_cndmask_b32_e32 v123, v123, v95, vcc
	v_add_u32_e32 v143, s56, v231
	ds_read_b64_tr_b16 v[80:81], v143 offset:0x0
	ds_read_b64_tr_b16 v[82:83], v143 offset:0x800
	ds_read_b64_tr_b16 v[84:85], v143 offset:0x1000
	ds_read_b64_tr_b16 v[86:87], v143 offset:0x1800
	ds_read_b64_tr_b16 v[88:89], v143 offset:0x2000
	ds_read_b64_tr_b16 v[90:91], v143 offset:0x2800
	ds_read_b64_tr_b16 v[92:93], v143 offset:0x3000
	ds_read_b64_tr_b16 v[94:95], v143 offset:0x3800
	v_add_f32_e32 v125, 0x41000000, v133
	v_add_f32_e32 v126, 0x41800000, v133
	v_add_f32_e32 v127, 0x41c00000, v133
	v_add_f32_e32 v128, 0x42000000, v133
	v_add_f32_e32 v129, 0x42200000, v133
	v_add_f32_e32 v130, 0x42400000, v133
	v_add_f32_e32 v131, 0x42600000, v133
	v_fma_f32 v116, v203, v133, v116
	v_fma_f32 v117, v203, v125, v117
	v_fma_f32 v118, v203, v126, v118
	v_fma_f32 v119, v203, v127, v119
	v_fma_f32 v120, v203, v128, v120
	v_fma_f32 v121, v203, v129, v121
	v_fma_f32 v122, v203, v130, v122
	v_fma_f32 v123, v203, v131, v123
	v_cmp_eq_u32_e32 vcc, 0, v134
	v_add_f32_e32 v138, 0x40faf233, v116
	v_cndmask_b32_e32 v116, v116, v138, vcc
	v_add_f32_e32 v138, 0x40faf233, v118
	v_cndmask_b32_e32 v118, v118, v138, vcc
	v_add_f32_e32 v138, 0x40faf233, v120
	v_cndmask_b32_e32 v120, v120, v138, vcc
	v_add_f32_e32 v138, 0x40faf233, v122
	v_cndmask_b32_e32 v122, v122, v138, vcc
	v_cmp_eq_u32_e32 vcc, 8, v134
	v_add_f32_e32 v138, 0x40faf233, v117
	v_cndmask_b32_e32 v117, v117, v138, vcc
	v_add_f32_e32 v138, 0x40faf233, v119
	v_cndmask_b32_e32 v119, v119, v138, vcc
	v_add_f32_e32 v138, 0x40faf233, v121
	v_cndmask_b32_e32 v121, v121, v138, vcc
	v_add_f32_e32 v138, 0x40faf233, v123
	v_cndmask_b32_e32 v123, v123, v138, vcc
	v_max3_f32 v0, v116, v117, v118
	v_max3_f32 v0, v0, v119, v120
	v_max3_f32 v0, v0, v121, v122
	v_max_f32_e32 v0, v0, v123
	v_mov_b32_e32 v2, v0
	s_nop 1
	v_permlane32_swap_b32_e32 v0, v2
	v_max_f32_e32 v2, v2, v2
	v_max_f32_e32 v0, v0, v0
	v_max_f32_e32 v0, v0, v2
	v_sub_f32_e32 v2, v0, v234
	v_mul_f32_e32 v2, 0x3db504f3, v2
	v_cmp_ge_f32_e32 vcc, s58, v2
	v_max_f32_e32 v2, v234, v234
	v_max_f32_e32 v0, v2, v0
	v_sub_f32_e32 v2, v234, v0
	v_mul_f32_e32 v2, 0x3e0293ee, v2
	v_exp_f32_e32 v2, v2
	s_cmp_eq_u64 vcc, exec
	s_cselect_b64 vcc, -1, 0
	v_cndmask_b32_e32 v14, v0, v234, vcc
	v_mul_f32_e32 v0, 0xbe0293ee, v14
	v_cndmask_b32_e64 v235, v2, 1.0, vcc
	v_fmamk_f32 v116, v116, 0x3e0293ee, v0
	v_fmamk_f32 v117, v117, 0x3e0293ee, v0
	v_fmamk_f32 v118, v118, 0x3e0293ee, v0
	v_fmamk_f32 v119, v119, 0x3e0293ee, v0
	v_fmamk_f32 v120, v120, 0x3e0293ee, v0
	v_fmamk_f32 v121, v121, 0x3e0293ee, v0
	v_fmamk_f32 v122, v122, 0x3e0293ee, v0
	v_fmamk_f32 v123, v123, 0x3e0293ee, v0
	v_exp_f32_e32 v116, v116
	v_exp_f32_e32 v117, v117
	v_exp_f32_e32 v118, v118
	v_exp_f32_e32 v119, v119
	v_exp_f32_e32 v120, v120
	v_exp_f32_e32 v121, v121
	v_exp_f32_e32 v122, v122
	v_exp_f32_e32 v123, v123
	v_and_b32_e32 v135, 1, v132
	v_lshlrev_b32_e32 v135, 4, v135
	v_add_f32_e32 v15, v116, v117
	v_add_f32_e32 v15, v118, v15
	v_add_f32_e32 v15, v119, v15
	v_add_f32_e32 v15, v120, v15
	v_add_f32_e32 v15, v121, v15
	v_add_f32_e32 v15, v122, v15
	v_add_f32_e32 v15, v123, v15
	v_mov_b32_e32 v0, v15
	s_nop 1
	v_permlane32_swap_b32_e32 v15, v0
	v_add_f32_e32 v15, v15, v0
	v_fmac_f32_e32 v15, v233, v235
	v_cmp_gt_u32_e32 vcc, 2, v132
	v_cvt_pk_bf16_f32 v136, v116, 0
	v_cvt_pk_bf16_f32 v137, v117, 0
	v_lshlrev_b32_e32 v136, v135, v136
	v_lshlrev_b32_e32 v137, v135, v137
	v_cndmask_b32_e32 v2, 0, v136, vcc
	v_cndmask_b32_e64 v3, v136, 0, vcc
	v_cndmask_b32_e32 v4, 0, v137, vcc
	v_cndmask_b32_e64 v5, v137, 0, vcc
	v_cvt_pk_bf16_f32 v136, v118, 0
	v_cvt_pk_bf16_f32 v137, v119, 0
	v_lshlrev_b32_e32 v136, v135, v136
	v_lshlrev_b32_e32 v137, v135, v137
	v_cndmask_b32_e32 v6, 0, v136, vcc
	v_cndmask_b32_e64 v7, v136, 0, vcc
	v_cndmask_b32_e32 v8, 0, v137, vcc
	v_cndmask_b32_e64 v9, v137, 0, vcc
	v_cvt_pk_bf16_f32 v136, v120, 0
	v_cvt_pk_bf16_f32 v137, v121, 0
	v_lshlrev_b32_e32 v136, v135, v136
	v_lshlrev_b32_e32 v137, v135, v137
	v_cndmask_b32_e32 v10, 0, v136, vcc
	v_cndmask_b32_e64 v11, v136, 0, vcc
	v_cndmask_b32_e32 v12, 0, v137, vcc
	v_cndmask_b32_e64 v13, v137, 0, vcc
	v_cvt_pk_bf16_f32 v136, v122, 0
	v_cvt_pk_bf16_f32 v137, v123, 0
	v_lshlrev_b32_e32 v136, v135, v136
	v_lshlrev_b32_e32 v137, v135, v137
	v_cndmask_b32_e32 v112, 0, v136, vcc
	v_cndmask_b32_e64 v113, v136, 0, vcc
	v_cndmask_b32_e32 v114, 0, v137, vcc
	v_cndmask_b32_e64 v115, v137, 0, vcc
	s_nop 1
	v_permlane32_swap_b32_e32 v2, v4
	v_permlane32_swap_b32_e32 v3, v5
	v_permlane32_swap_b32_e32 v6, v8
	v_permlane32_swap_b32_e32 v7, v9
	v_permlane32_swap_b32_e32 v10, v12
	v_permlane32_swap_b32_e32 v11, v13
	v_permlane32_swap_b32_e32 v112, v114
	v_permlane32_swap_b32_e32 v113, v115
	v_add_u32_e32 v0, s56, v231
	v_cmp_gt_f32_e32 vcc, 1.0, v235
	s_cbranch_vccnz .LBB0_335
	s_branch .Lpv_reads_done
; template <int CLS> __device__ __forceinline__ void bias_tile(f32x16& p0, f32x16& p1, int dq, float slr, int dq15, int dq3) {
;     ...
;             else { const bool n5 = dq <= C + 512; const float b16 = n5 ? L2R : 0.f, b4 = n5 ? 0.f : NEG; v += m16 ? b16 : (m4 ? b4 : NEG); }
; __device__ __forceinline__ void attn_block(const bf16_t* __restrict__ proj, bf16_t* __restrict__ mixed, int b, int h, int qb, char* lds) {
;     ...
;                 const float NEG = -__builtin_inff();
;                 float e0 = FA_SEL8(p0, 0) + fc0, e1 = FA_SEL8(p0, 8) + (fc0 + 16.f * slr), e2 = FA_SEL8(p1, 0) + (fc0 + 32.f * slr), e3 = FA_SEL8(p1, 8) + (fc0 + 48.f * slr);
;     ...
;                 e0 = lane_valid ? e0 : NEG; e1 = lane_valid ? e1 : NEG; e2 = lane_valid ? e2 : NEG; e3 = lane_valid ? e3 : NEG;
;                 float pmax = fmaxf(fmaxf(e0, e1), fmaxf(e2, e3));
;                 { auto rr = __builtin_amdgcn_permlane32_swap(__float_as_uint(pmax), __float_as_uint(pmax), false, false); pmax = fmaxf(__uint_as_float(rr[0]), __uint_as_float(rr[1])); }
;                 constexpr float C2 = LOG2E * SCALE; float mn;
;                 if (__builtin_expect(__all((pmax - m_reg) * SCALE <= THR), 1)) { mn = m_reg; alpha = 1.f; }
;                 else { mn = fmaxf(m_reg, pmax); alpha = __builtin_amdgcn_exp2f((m_reg - mn) * C2); m_reg = mn; }
;                 const float mnL = -mn * C2;
;                 e0 = __builtin_amdgcn_exp2f(__builtin_fmaf(e0, C2, mnL)); e1 = __builtin_amdgcn_exp2f(__builtin_fmaf(e1, C2, mnL));
;                 e2 = __builtin_amdgcn_exp2f(__builtin_fmaf(e2, C2, mnL)); e3 = __builtin_amdgcn_exp2f(__builtin_fmaf(e3, C2, mnL));
;                 float ps = (e0 + e1) + (e2 + e3);
;                 { auto rr = __builtin_amdgcn_permlane32_swap(__float_as_uint(ps), __float_as_uint(ps), false, false); ps = __uint_as_float(rr[0]) + __uint_as_float(rr[1]); }
;                 l_reg = l_reg * alpha + ps;
;     ...
;                 FA_SCAT(e0, pa0); FA_SCAT(e1, pa1); FA_SCAT(e2, pa2); FA_SCAT(e3, pa3);
.Lstr512_fast:
	s_nop 3
	v_and_b32_e32 v132, 3, v0
	v_and_b32_e32 v134, 12, v0
	v_cvt_f32_u32_e32 v133, v132
	v_cmp_eq_u32_e32 vcc, 1, v132
	v_cndmask_b32_e32 v116, v96, v97, vcc
	v_cndmask_b32_e32 v117, v100, v101, vcc
	v_cndmask_b32_e32 v118, v104, v105, vcc
	v_cndmask_b32_e32 v119, v108, v109, vcc
	v_cndmask_b32_e32 v120, v80, v81, vcc
	v_cndmask_b32_e32 v121, v84, v85, vcc
	v_cndmask_b32_e32 v122, v88, v89, vcc
	v_cndmask_b32_e32 v123, v92, v93, vcc
	v_cmp_eq_u32_e32 vcc, 2, v132
	v_cndmask_b32_e32 v116, v116, v98, vcc
	v_cndmask_b32_e32 v117, v117, v102, vcc
	v_cndmask_b32_e32 v118, v118, v106, vcc
	v_cndmask_b32_e32 v119, v119, v110, vcc
	v_cndmask_b32_e32 v120, v120, v82, vcc
	v_cndmask_b32_e32 v121, v121, v86, vcc
	v_cndmask_b32_e32 v122, v122, v90, vcc
	v_cndmask_b32_e32 v123, v123, v94, vcc
	v_cmp_eq_u32_e32 vcc, 3, v132
	v_cndmask_b32_e32 v116, v116, v99, vcc
	v_cndmask_b32_e32 v117, v117, v103, vcc
	v_cndmask_b32_e32 v118, v118, v107, vcc
	v_cndmask_b32_e32 v119, v119, v111, vcc
	v_cndmask_b32_e32 v120, v120, v83, vcc
	v_cndmask_b32_e32 v121, v121, v87, vcc
	v_cndmask_b32_e32 v122, v122, v91, vcc
	v_cndmask_b32_e32 v123, v123, v95, vcc
	v_add_u32_e32 v143, s56, v231
	ds_read_b64_tr_b16 v[80:81], v143 offset:0x0
	ds_read_b64_tr_b16 v[82:83], v143 offset:0x800
	ds_read_b64_tr_b16 v[84:85], v143 offset:0x1000
	ds_read_b64_tr_b16 v[86:87], v143 offset:0x1800
	ds_read_b64_tr_b16 v[88:89], v143 offset:0x2000
	ds_read_b64_tr_b16 v[90:91], v143 offset:0x2800
	ds_read_b64_tr_b16 v[92:93], v143 offset:0x3000
	ds_read_b64_tr_b16 v[94:95], v143 offset:0x3800
	v_add_f32_e32 v125, 0x41000000, v133
	v_add_f32_e32 v126, 0x41800000, v133
	v_add_f32_e32 v127, 0x41c00000, v133
	v_add_f32_e32 v128, 0x42000000, v133
	v_add_f32_e32 v129, 0x42200000, v133
	v_add_f32_e32 v130, 0x42400000, v133
	v_add_f32_e32 v131, 0x42600000, v133
	v_fma_f32 v116, v203, v133, v116
	v_fma_f32 v117, v203, v125, v117
	v_fma_f32 v118, v203, v126, v118
	v_fma_f32 v119, v203, v127, v119
	v_fma_f32 v120, v203, v128, v120
	v_fma_f32 v121, v203, v129, v121
	v_fma_f32 v122, v203, v130, v122
	v_fma_f32 v123, v203, v131, v123
	v_sub_u32_e32 v139, v0, v132
	v_mov_b32_e32 v140, 0x40faf233
	v_cmp_eq_u32_e64 s[96:97], 0, v134
	s_nop 1
	v_cmp_ge_i32_e32 vcc, 0x200, v139
	v_cndmask_b32_e32 v141, 0, v140, vcc
	v_cndmask_b32_e64 v142, v187, 0, vcc
	v_cndmask_b32_e64 v141, v142, v141, s[96:97]
	v_add_f32_e32 v116, v116, v141
	v_cmp_ge_i32_e32 vcc, 0x210, v139
	v_cndmask_b32_e32 v141, 0, v140, vcc
	v_cndmask_b32_e64 v142, v187, 0, vcc
	v_cndmask_b32_e64 v141, v142, v141, s[96:97]
	v_add_f32_e32 v118, v118, v141
	v_cmp_ge_i32_e32 vcc, 0x220, v139
	v_cndmask_b32_e32 v141, 0, v140, vcc
	v_cndmask_b32_e64 v142, v187, 0, vcc
	v_cndmask_b32_e64 v141, v142, v141, s[96:97]
	v_add_f32_e32 v120, v120, v141
	v_cmp_ge_i32_e32 vcc, 0x230, v139
	v_cndmask_b32_e32 v141, 0, v140, vcc
	v_cndmask_b32_e64 v142, v187, 0, vcc
	v_cndmask_b32_e64 v141, v142, v141, s[96:97]
	v_add_f32_e32 v122, v122, v141
	v_cmp_eq_u32_e64 s[96:97], 8, v134
	s_nop 1
	v_cmp_ge_i32_e32 vcc, 0x208, v139
	v_cndmask_b32_e32 v141, 0, v140, vcc
	v_cndmask_b32_e64 v142, v187, 0, vcc
	v_cndmask_b32_e64 v141, v142, v141, s[96:97]
	v_add_f32_e32 v117, v117, v141
	v_cmp_ge_i32_e32 vcc, 0x218, v139
	v_cndmask_b32_e32 v141, 0, v140, vcc
	v_cndmask_b32_e64 v142, v187, 0, vcc
	v_cndmask_b32_e64 v141, v142, v141, s[96:97]
	v_add_f32_e32 v119, v119, v141
	v_cmp_ge_i32_e32 vcc, 0x228, v139
	v_cndmask_b32_e32 v141, 0, v140, vcc
	v_cndmask_b32_e64 v142, v187, 0, vcc
	v_cndmask_b32_e64 v141, v142, v141, s[96:97]
	v_add_f32_e32 v121, v121, v141
	v_cmp_ge_i32_e32 vcc, 0x238, v139
	v_cndmask_b32_e32 v141, 0, v140, vcc
	v_cndmask_b32_e64 v142, v187, 0, vcc
	v_cndmask_b32_e64 v141, v142, v141, s[96:97]
	v_add_f32_e32 v123, v123, v141
	v_max3_f32 v0, v116, v117, v118
	v_max3_f32 v0, v0, v119, v120
	v_max3_f32 v0, v0, v121, v122
	v_max_f32_e32 v0, v0, v123
	v_mov_b32_e32 v2, v0
	s_nop 1
	v_permlane32_swap_b32_e32 v0, v2
	v_max_f32_e32 v2, v2, v2
	v_max_f32_e32 v0, v0, v0
	v_max_f32_e32 v0, v0, v2
	v_sub_f32_e32 v2, v0, v234
	v_mul_f32_e32 v2, 0x3db504f3, v2
	v_cmp_ge_f32_e32 vcc, s58, v2
	v_max_f32_e32 v2, v234, v234
	v_max_f32_e32 v0, v2, v0
	v_sub_f32_e32 v2, v234, v0
	v_mul_f32_e32 v2, 0x3e0293ee, v2
	v_exp_f32_e32 v2, v2
	s_cmp_eq_u64 vcc, exec
	s_cselect_b64 vcc, -1, 0
	v_cndmask_b32_e32 v14, v0, v234, vcc
	v_mul_f32_e32 v0, 0xbe0293ee, v14
	v_cndmask_b32_e64 v235, v2, 1.0, vcc
	v_fmamk_f32 v116, v116, 0x3e0293ee, v0
	v_fmamk_f32 v117, v117, 0x3e0293ee, v0
	v_fmamk_f32 v118, v118, 0x3e0293ee, v0
	v_fmamk_f32 v119, v119, 0x3e0293ee, v0
	v_fmamk_f32 v120, v120, 0x3e0293ee, v0
	v_fmamk_f32 v121, v121, 0x3e0293ee, v0
	v_fmamk_f32 v122, v122, 0x3e0293ee, v0
	v_fmamk_f32 v123, v123, 0x3e0293ee, v0
	v_exp_f32_e32 v116, v116
	v_exp_f32_e32 v117, v117
	v_exp_f32_e32 v118, v118
	v_exp_f32_e32 v119, v119
	v_exp_f32_e32 v120, v120
	v_exp_f32_e32 v121, v121
	v_exp_f32_e32 v122, v122
	v_exp_f32_e32 v123, v123
	v_and_b32_e32 v135, 1, v132
	v_lshlrev_b32_e32 v135, 4, v135
	v_add_f32_e32 v15, v116, v117
	v_add_f32_e32 v15, v118, v15
	v_add_f32_e32 v15, v119, v15
	v_add_f32_e32 v15, v120, v15
	v_add_f32_e32 v15, v121, v15
	v_add_f32_e32 v15, v122, v15
	v_add_f32_e32 v15, v123, v15
	v_mov_b32_e32 v0, v15
	s_nop 1
	v_permlane32_swap_b32_e32 v15, v0
	v_add_f32_e32 v15, v15, v0
	v_fmac_f32_e32 v15, v233, v235
	v_cmp_gt_u32_e32 vcc, 2, v132
	v_cvt_pk_bf16_f32 v136, v116, 0
	v_cvt_pk_bf16_f32 v137, v117, 0
	v_lshlrev_b32_e32 v136, v135, v136
	v_lshlrev_b32_e32 v137, v135, v137
	v_cndmask_b32_e32 v2, 0, v136, vcc
	v_cndmask_b32_e64 v3, v136, 0, vcc
	v_cndmask_b32_e32 v4, 0, v137, vcc
	v_cndmask_b32_e64 v5, v137, 0, vcc
	v_cvt_pk_bf16_f32 v136, v118, 0
	v_cvt_pk_bf16_f32 v137, v119, 0
	v_lshlrev_b32_e32 v136, v135, v136
	v_lshlrev_b32_e32 v137, v135, v137
	v_cndmask_b32_e32 v6, 0, v136, vcc
	v_cndmask_b32_e64 v7, v136, 0, vcc
	v_cndmask_b32_e32 v8, 0, v137, vcc
	v_cndmask_b32_e64 v9, v137, 0, vcc
	v_cvt_pk_bf16_f32 v136, v120, 0
	v_cvt_pk_bf16_f32 v137, v121, 0
	v_lshlrev_b32_e32 v136, v135, v136
	v_lshlrev_b32_e32 v137, v135, v137
	v_cndmask_b32_e32 v10, 0, v136, vcc
	v_cndmask_b32_e64 v11, v136, 0, vcc
	v_cndmask_b32_e32 v12, 0, v137, vcc
	v_cndmask_b32_e64 v13, v137, 0, vcc
	v_cvt_pk_bf16_f32 v136, v122, 0
	v_cvt_pk_bf16_f32 v137, v123, 0
	v_lshlrev_b32_e32 v136, v135, v136
	v_lshlrev_b32_e32 v137, v135, v137
	v_cndmask_b32_e32 v112, 0, v136, vcc
	v_cndmask_b32_e64 v113, v136, 0, vcc
	v_cndmask_b32_e32 v114, 0, v137, vcc
	v_cndmask_b32_e64 v115, v137, 0, vcc
	s_nop 1
	v_permlane32_swap_b32_e32 v2, v4
	v_permlane32_swap_b32_e32 v3, v5
	v_permlane32_swap_b32_e32 v6, v8
	v_permlane32_swap_b32_e32 v7, v9
	v_permlane32_swap_b32_e32 v10, v12
	v_permlane32_swap_b32_e32 v11, v13
	v_permlane32_swap_b32_e32 v112, v114
	v_permlane32_swap_b32_e32 v113, v115
	v_add_u32_e32 v0, s56, v231
	v_cmp_gt_f32_e32 vcc, 1.0, v235
	s_cbranch_vccnz .LBB0_335
	s_branch .Lpv_reads_done
; __device__ __forceinline__ void attn_block(const bf16_t* __restrict__ proj, bf16_t* __restrict__ mixed, int b, int h, int qb, char* lds) {
;     ...
;                 const float NEG = -__builtin_inff();
;                 float e0 = FA_SEL8(p0, 0) + fc0, e1 = FA_SEL8(p0, 8) + (fc0 + 16.f * slr), e2 = FA_SEL8(p1, 0) + (fc0 + 32.f * slr), e3 = FA_SEL8(p1, 8) + (fc0 + 48.f * slr);
;     ...
;                 e0 = lane_valid ? e0 : NEG; e1 = lane_valid ? e1 : NEG; e2 = lane_valid ? e2 : NEG; e3 = lane_valid ? e3 : NEG;
;                 float pmax = fmaxf(fmaxf(e0, e1), fmaxf(e2, e3));
;                 { auto rr = __builtin_amdgcn_permlane32_swap(__float_as_uint(pmax), __float_as_uint(pmax), false, false); pmax = fmaxf(__uint_as_float(rr[0]), __uint_as_float(rr[1])); }
;                 constexpr float C2 = LOG2E * SCALE; float mn;
;                 if (__builtin_expect(__all((pmax - m_reg) * SCALE <= THR), 1)) { mn = m_reg; alpha = 1.f; }
;                 else { mn = fmaxf(m_reg, pmax); alpha = __builtin_amdgcn_exp2f((m_reg - mn) * C2); m_reg = mn; }
;                 const float mnL = -mn * C2;
;                 e0 = __builtin_amdgcn_exp2f(__builtin_fmaf(e0, C2, mnL)); e1 = __builtin_amdgcn_exp2f(__builtin_fmaf(e1, C2, mnL));
;                 e2 = __builtin_amdgcn_exp2f(__builtin_fmaf(e2, C2, mnL)); e3 = __builtin_amdgcn_exp2f(__builtin_fmaf(e3, C2, mnL));
;                 float ps = (e0 + e1) + (e2 + e3);
;                 { auto rr = __builtin_amdgcn_permlane32_swap(__float_as_uint(ps), __float_as_uint(ps), false, false); ps = __uint_as_float(rr[0]) + __uint_as_float(rr[1]); }
;                 l_reg = l_reg * alpha + ps;
;     ...
;                 FA_SCAT(e0, pa0); FA_SCAT(e1, pa1); FA_SCAT(e2, pa2); FA_SCAT(e3, pa3);
.LBB0_334:
	s_nop 8
	v_cndmask_b32_e64 v3, v80, v81, s[4:5]
	v_cndmask_b32_e64 v4, v88, v89, s[4:5]
	v_cndmask_b32_e64 v0, v96, v97, s[4:5]
	v_cndmask_b32_e64 v2, v104, v105, s[4:5]
	v_cndmask_b32_e64 v3, v3, v82, s[6:7]
	v_cndmask_b32_e64 v4, v4, v90, s[6:7]
	v_cndmask_b32_e64 v0, v0, v98, s[6:7]
	v_cndmask_b32_e64 v2, v2, v106, s[6:7]
	v_cndmask_b32_e64 v3, v3, v83, s[8:9]
	v_cndmask_b32_e64 v4, v4, v91, s[8:9]
	v_cndmask_b32_e64 v0, v0, v99, s[8:9]
	v_cndmask_b32_e64 v2, v2, v107, s[8:9]
	v_cndmask_b32_e64 v3, v3, v84, s[10:11]
	v_cndmask_b32_e64 v4, v4, v92, s[10:11]
	v_cndmask_b32_e64 v0, v0, v100, s[10:11]
	v_cndmask_b32_e64 v2, v2, v108, s[10:11]
	v_cndmask_b32_e64 v3, v3, v85, s[12:13]
	v_cndmask_b32_e64 v4, v4, v93, s[12:13]
	v_cndmask_b32_e64 v0, v0, v101, s[12:13]
	v_cndmask_b32_e64 v2, v2, v109, s[12:13]
	v_cndmask_b32_e64 v3, v3, v86, s[14:15]
	v_cndmask_b32_e64 v4, v4, v94, s[14:15]
	v_cndmask_b32_e64 v0, v0, v102, s[14:15]
	v_cndmask_b32_e64 v2, v2, v110, s[14:15]
	v_cndmask_b32_e64 v3, v3, v87, s[16:17]
	v_cndmask_b32_e64 v4, v4, v95, s[16:17]
	v_cndmask_b32_e64 v0, v0, v103, s[16:17]
	v_cndmask_b32_e64 v2, v2, v111, s[16:17]
	v_add_u32_e32 v143, s56, v231
	ds_read_b64_tr_b16 v[80:81], v143 offset:0x0
	ds_read_b64_tr_b16 v[82:83], v143 offset:0x800
	ds_read_b64_tr_b16 v[84:85], v143 offset:0x1000
	ds_read_b64_tr_b16 v[86:87], v143 offset:0x1800
	ds_read_b64_tr_b16 v[88:89], v143 offset:0x2000
	ds_read_b64_tr_b16 v[90:91], v143 offset:0x2800
	ds_read_b64_tr_b16 v[92:93], v143 offset:0x3000
	ds_read_b64_tr_b16 v[94:95], v143 offset:0x3800
	v_add_f32_e32 v3, v228, v3
	v_add_f32_e32 v4, v229, v4
	v_add_f32_e32 v0, v212, v0
	v_add_f32_e32 v2, v227, v2
	v_cndmask_b32_e64 v3, v187, v3, s[0:1]
	v_cndmask_b32_e64 v4, v187, v4, s[0:1]
	v_cndmask_b32_e64 v0, v187, v0, s[0:1]
	v_cndmask_b32_e64 v2, v187, v2, s[0:1]
	v_max_f32_e32 v5, v3, v4
	v_max3_f32 v5, v0, v2, v5
	v_mov_b32_e32 v6, v5
	s_nop 1
	v_permlane32_swap_b32_e32 v5, v6
	v_max_f32_e32 v6, v6, v6
	v_max_f32_e32 v5, v5, v5
	v_max_f32_e32 v5, v5, v6
	v_sub_f32_e32 v6, v5, v234
	v_mul_f32_e32 v6, 0x3db504f3, v6
	v_cmp_ge_f32_e32 vcc, s58, v6
	s_cmp_eq_u64 vcc, exec
	v_max_f32_e32 v6, v234, v234
	v_max_f32_e32 v5, v6, v5
	s_cselect_b64 vcc, -1, 0
	v_cndmask_b32_e32 v14, v5, v234, vcc
	v_sub_f32_e32 v6, v234, v5
	v_mul_f32_e32 v5, 0xbe0293ee, v14
	v_fmamk_f32 v0, v0, 0x3e0293ee, v5
	v_exp_f32_e32 v10, v0
	v_fmamk_f32 v0, v2, 0x3e0293ee, v5
	v_exp_f32_e32 v116, v0
	v_fmamk_f32 v0, v3, 0x3e0293ee, v5
	v_fmac_f32_e32 v5, 0x3e0293ee, v4
	v_exp_f32_e32 v11, v0
	v_exp_f32_e32 v117, v5
	v_mul_f32_e32 v6, 0x3e0293ee, v6
	v_exp_f32_e32 v6, v6
	v_pk_add_f32 v[2:3], v[10:11], v[116:117]
	s_nop 0
	v_pk_add_f32 v[2:3], v[2:3], v[2:3] op_sel:[0,1] op_sel_hi:[1,0]
	v_cndmask_b32_e64 v235, v6, 1.0, vcc
	v_mov_b32_e32 v0, v2
	s_nop 1
	v_permlane32_swap_b32_e32 v2, v0
	v_add_f32_e32 v15, v2, v0
	v_cvt_pk_bf16_f32 v0, v10, v1
	v_fmac_f32_e32 v15, v233, v235
	v_lshlrev_b32_e32 v0, v230, v0
	v_cndmask_b32_e64 v2, 0, v0, s[18:19]
	v_cndmask_b32_e64 v3, 0, v0, s[20:21]
	v_cndmask_b32_e64 v4, 0, v0, s[22:23]
	v_cndmask_b32_e64 v5, 0, v0, s[24:25]
	v_cvt_pk_bf16_f32 v0, v116, v1
	s_nop 0
	v_permlane32_swap_b32_e32 v2, v4
	v_lshlrev_b32_e32 v0, v230, v0
	v_cndmask_b32_e64 v6, 0, v0, s[18:19]
	v_cndmask_b32_e64 v7, 0, v0, s[20:21]
	v_cndmask_b32_e64 v8, 0, v0, s[22:23]
	v_cndmask_b32_e64 v9, 0, v0, s[24:25]
	v_cvt_pk_bf16_f32 v0, v11, v1
	v_permlane32_swap_b32_e32 v3, v5
	v_lshlrev_b32_e32 v0, v230, v0
	v_cndmask_b32_e64 v10, 0, v0, s[18:19]
	v_cndmask_b32_e64 v11, 0, v0, s[20:21]
	v_cndmask_b32_e64 v12, 0, v0, s[22:23]
	v_cndmask_b32_e64 v13, 0, v0, s[24:25]
	v_cvt_pk_bf16_f32 v0, v117, v1
	v_permlane32_swap_b32_e32 v6, v8
	v_lshlrev_b32_e32 v0, v230, v0
	v_cndmask_b32_e64 v112, 0, v0, s[18:19]
	v_cndmask_b32_e64 v113, 0, v0, s[20:21]
	v_cndmask_b32_e64 v114, 0, v0, s[22:23]
	v_cndmask_b32_e64 v115, 0, v0, s[24:25]
	v_permlane32_swap_b32_e32 v7, v9
	v_permlane32_swap_b32_e32 v10, v12
	v_permlane32_swap_b32_e32 v11, v13
	v_permlane32_swap_b32_e32 v112, v114
	v_permlane32_swap_b32_e32 v113, v115
	v_add_u32_e32 v0, s56, v231
	v_cmp_gt_f32_e32 vcc, 1.0, v235
	s_cbranch_vccz .Lpv_reads_done

; template <int KS, int HF>
; __device__ __forceinline__ void pv_tile(f32x16* o, int vb, bf16x8 pa0, bf16x8 pa1, bf16x8 pa2, bf16x8 pa3) {
;     ...
;     FA_PV_D0(0); FA_PV_D0(1); FA_PV_D0(2); FA_PV_D0(3);
.Lpv_reads_done:
	s_waitcnt lgkmcnt(0)
	s_nop 4
	v_mfma_f32_32x32x16_bf16 v[64:79], v[2:5], v[80:83], v[64:79]
	ds_read_b64_tr_b16 v[80:81], v0 offset:0x200
	ds_read_b64_tr_b16 v[82:83], v0 offset:0xa00
	v_mfma_f32_32x32x16_bf16 v[64:79], v[6:9], v[84:87], v[64:79]
	ds_read_b64_tr_b16 v[84:85], v0 offset:0x1200
	ds_read_b64_tr_b16 v[86:87], v0 offset:0x1a00
	v_mfma_f32_32x32x16_bf16 v[64:79], v[10:13], v[88:91], v[64:79]
	ds_read_b64_tr_b16 v[88:89], v0 offset:0x2200
	ds_read_b64_tr_b16 v[90:91], v0 offset:0x2a00
	v_mfma_f32_32x32x16_bf16 v[64:79], v[112:115], v[92:95], v[64:79]
	ds_read_b64_tr_b16 v[92:93], v0 offset:0x3200
	ds_read_b64_tr_b16 v[94:95], v0 offset:0x3a00
	s_waitcnt lgkmcnt(0)
	v_mfma_f32_32x32x16_bf16 v[48:63], v[2:5], v[80:83], v[48:63]
	ds_read_b64_tr_b16 v[80:81], v0 offset:0x400
	ds_read_b64_tr_b16 v[82:83], v0 offset:0xc00
	v_mfma_f32_32x32x16_bf16 v[48:63], v[6:9], v[84:87], v[48:63]
	ds_read_b64_tr_b16 v[84:85], v0 offset:0x1400
	ds_read_b64_tr_b16 v[86:87], v0 offset:0x1c00
	v_mfma_f32_32x32x16_bf16 v[48:63], v[10:13], v[88:91], v[48:63]
	ds_read_b64_tr_b16 v[88:89], v0 offset:0x2400
	ds_read_b64_tr_b16 v[90:91], v0 offset:0x2c00
	v_mfma_f32_32x32x16_bf16 v[48:63], v[112:115], v[92:95], v[48:63]
	ds_read_b64_tr_b16 v[92:93], v0 offset:0x3400
	ds_read_b64_tr_b16 v[94:95], v0 offset:0x3c00
	s_waitcnt lgkmcnt(0)
	v_mfma_f32_32x32x16_bf16 v[32:47], v[2:5], v[80:83], v[32:47]
	ds_read_b64_tr_b16 v[80:81], v0 offset:0x600
	ds_read_b64_tr_b16 v[82:83], v0 offset:0xe00
	v_mfma_f32_32x32x16_bf16 v[32:47], v[6:9], v[84:87], v[32:47]
	ds_read_b64_tr_b16 v[84:85], v0 offset:0x1600
	ds_read_b64_tr_b16 v[86:87], v0 offset:0x1e00
	v_mfma_f32_32x32x16_bf16 v[32:47], v[10:13], v[88:91], v[32:47]
	ds_read_b64_tr_b16 v[88:89], v0 offset:0x2600
	ds_read_b64_tr_b16 v[90:91], v0 offset:0x2e00
	v_mfma_f32_32x32x16_bf16 v[32:47], v[112:115], v[92:95], v[32:47]
	ds_read_b64_tr_b16 v[92:93], v0 offset:0x3600
	ds_read_b64_tr_b16 v[94:95], v0 offset:0x3e00
	s_waitcnt lgkmcnt(0)
	v_mfma_f32_32x32x16_bf16 v[16:31], v[2:5], v[80:83], v[16:31]
	v_mfma_f32_32x32x16_bf16 v[16:31], v[6:9], v[84:87], v[16:31]
	v_mfma_f32_32x32x16_bf16 v[16:31], v[10:13], v[88:91], v[16:31]
	v_mfma_f32_32x32x16_bf16 v[16:31], v[112:115], v[92:95], v[16:31]
